# v021_g2pipe
# baseline (speedup 1.0000x reference)
; #define SCHED __builtin_amdgcn_sched_barrier(0)
; __device__ __forceinline__ void phase_gemm2(const Params& p, int layer, const float* xold, float* xnew) {
;     ...
; #pragma unroll
;     for (int ai = 0; ai < 2; ++ai)
; #pragma unroll
;       for (int bj = 0; bj < 2; ++bj) {
;         f32x4 xo[4][2];
; #pragma unroll
;         for (int m = 0; m < 4; ++m)
; #pragma unroll
;           for (int n = 0; n < 2; ++n) {
;             int feat = feat0 + ai * 128 + wr * 64 + m * 16 + fq * 4;
;             int tok = tok0 + bj * 128 + wc * 32 + n * 16 + fr;
;             xo[m][n] = *reinterpret_cast<const f32x4*>(xold + (size_t)tok * DM + feat);
;           }
;         SCHED;
; #pragma unroll
;         for (int m = 0; m < 4; ++m)
; #pragma unroll
;           for (int n = 0; n < 2; ++n) {
;             int feat = feat0 + ai * 128 + wr * 64 + m * 16 + fq * 4;
;             int tok = tok0 + bj * 128 + wc * 32 + n * 16 + fr;
;             *reinterpret_cast<f32x4*>(xnew + (size_t)tok * DM + feat) = xo[m][n] + acc[ai][bj][m][n];
.LBB0_34:
	s_or_b64 exec, exec, s[18:19]
	v_lshrrev_b32_e32 v130, 4, v97
	v_lshlrev_b32_e32 v130, 2, v130
	v_lshrrev_b32_e32 v97, 1, v97
	v_and_or_b32 v130, v130, 12, v147
	v_and_b32_e32 v97, 0x60, v97
	v_add_u32_e32 v134, s16, v130
	v_or3_b32 v160, v97, v146, s14
	v_and_b32_e32 v140, 15, v210
	v_bfe_u32 v141, v210, 4, 2
	v_lshrrev_b32_e32 v142, 6, v210
	v_sub_u32_e32 v143, v160, v140
	v_lshlrev_b32_e32 v144, 2, v141
	v_sub_u32_e32 v144, v134, v144
	v_add_u32_e32 v143, v143, v141
	v_lshl_add_u32 v144, v140, 2, v144
	v_lshlrev_b32_e32 v143, 14, v143
	v_lshl_add_u32 v130, v144, 2, v143
	v_add_u32_e32 v131, 0x10000, v130
	v_add_u32_e32 v132, 0x20000, v130
	v_add_u32_e32 v133, 0x30000, v130
	v_add_u32_e32 v134, 0x40000, v130
	v_add_u32_e32 v135, 0x50000, v130
	v_add_u32_e32 v136, 0x60000, v130
	v_add_u32_e32 v137, 0x70000, v130
	v_mul_u32_u24_e32 v142, 0x2200, v142
	v_mul_u32_u24_e32 v145, 0x110, v140
	v_lshl_add_u32 v145, v141, 4, v145
	v_add3_u32 v138, v142, v145, 32
	v_mul_u32_u24_e32 v145, 0x110, v141
	v_lshl_add_u32 v145, v140, 4, v145
	v_add3_u32 v139, v142, v145, 32
	s_add_u32 s16, s10, 0x200000
	s_addc_u32 s17, s11, 0
	s_mov_b64 s[14:15], s[8:9]
	global_load_dwordx4 v[164:167], v130, s[14:15] offset:0
	global_load_dwordx4 v[168:171], v131, s[14:15] offset:0
	global_load_dwordx4 v[172:175], v132, s[14:15] offset:0
	global_load_dwordx4 v[176:179], v133, s[14:15] offset:0
	global_load_dwordx4 v[180:183], v134, s[14:15] offset:0
	global_load_dwordx4 v[184:187], v135, s[14:15] offset:0
	global_load_dwordx4 v[188:191], v136, s[14:15] offset:0
	global_load_dwordx4 v[192:195], v137, s[14:15] offset:0
	s_mov_b64 s[14:15], s[8:9]
	global_load_dwordx4 v[140:143], v130, s[14:15] offset:512
	global_load_dwordx4 v[144:147], v131, s[14:15] offset:512
	global_load_dwordx4 v[148:151], v132, s[14:15] offset:512
	global_load_dwordx4 v[152:155], v133, s[14:15] offset:512
	global_load_dwordx4 v[156:159], v134, s[14:15] offset:512
	global_load_dwordx4 v[196:199], v135, s[14:15] offset:512
	global_load_dwordx4 v[200:203], v136, s[14:15] offset:512
	global_load_dwordx4 v[204:207], v137, s[14:15] offset:512
	ds_write_b128 v138, v[126:129] offset:0
	ds_write_b128 v138, v[122:125] offset:4352
	ds_write_b128 v138, v[118:121] offset:64
	ds_write_b128 v138, v[114:117] offset:4416
	ds_write_b128 v138, v[110:113] offset:128
	ds_write_b128 v138, v[106:109] offset:4480
	ds_write_b128 v138, v[102:105] offset:192
	ds_write_b128 v138, v[98:101] offset:4544
	ds_read_b128 v[222:225], v139 offset:0
	ds_read_b128 v[226:229], v139 offset:1088
	ds_read_b128 v[230:233], v139 offset:2176
	ds_read_b128 v[234:237], v139 offset:3264
	ds_read_b128 v[238:241], v139 offset:4352
	ds_read_b128 v[242:245], v139 offset:5440
	ds_read_b128 v[246:249], v139 offset:6528
	ds_read_b128 v[250:253], v139 offset:7616
	s_waitcnt lgkmcnt(0)
	s_waitcnt vmcnt(15)
	v_pk_add_f32 v[222:223], v[222:223], v[164:165]
	v_pk_add_f32 v[224:225], v[224:225], v[166:167]
	global_store_dwordx4 v130, v[222:225], s[10:11] offset:0
	s_waitcnt vmcnt(15)
	v_pk_add_f32 v[226:227], v[226:227], v[168:169]
	v_pk_add_f32 v[228:229], v[228:229], v[170:171]
	global_store_dwordx4 v131, v[226:229], s[10:11] offset:0
	s_waitcnt vmcnt(15)
	v_pk_add_f32 v[230:231], v[230:231], v[172:173]
	v_pk_add_f32 v[232:233], v[232:233], v[174:175]
	global_store_dwordx4 v132, v[230:233], s[10:11] offset:0
	s_waitcnt vmcnt(15)
	v_pk_add_f32 v[234:235], v[234:235], v[176:177]
	v_pk_add_f32 v[236:237], v[236:237], v[178:179]
	global_store_dwordx4 v133, v[234:237], s[10:11] offset:0
	s_waitcnt vmcnt(15)
	v_pk_add_f32 v[238:239], v[238:239], v[180:181]
	v_pk_add_f32 v[240:241], v[240:241], v[182:183]
	global_store_dwordx4 v134, v[238:241], s[10:11] offset:0
	s_waitcnt vmcnt(15)
	v_pk_add_f32 v[242:243], v[242:243], v[184:185]
	v_pk_add_f32 v[244:245], v[244:245], v[186:187]
	global_store_dwordx4 v135, v[242:245], s[10:11] offset:0
	s_waitcnt vmcnt(15)
	v_pk_add_f32 v[246:247], v[246:247], v[188:189]
	v_pk_add_f32 v[248:249], v[248:249], v[190:191]
	global_store_dwordx4 v136, v[246:249], s[10:11] offset:0
	s_waitcnt vmcnt(15)
	v_pk_add_f32 v[250:251], v[250:251], v[192:193]
	v_pk_add_f32 v[252:253], v[252:253], v[194:195]
	global_store_dwordx4 v137, v[250:253], s[10:11] offset:0
	s_add_u32 s14, s8, 0x200000
	s_addc_u32 s15, s9, 0
	global_load_dwordx4 v[164:167], v130, s[14:15] offset:0
	global_load_dwordx4 v[168:171], v131, s[14:15] offset:0
	global_load_dwordx4 v[172:175], v132, s[14:15] offset:0
	global_load_dwordx4 v[176:179], v133, s[14:15] offset:0
	global_load_dwordx4 v[180:183], v134, s[14:15] offset:0
	global_load_dwordx4 v[184:187], v135, s[14:15] offset:0
	global_load_dwordx4 v[188:191], v136, s[14:15] offset:0
	global_load_dwordx4 v[192:195], v137, s[14:15] offset:0
	ds_write_b128 v138, v[60:63] offset:0
	ds_write_b128 v138, v[56:59] offset:4352
	ds_write_b128 v138, v[52:55] offset:64
	ds_write_b128 v138, v[48:51] offset:4416
	ds_write_b128 v138, v[44:47] offset:128
	ds_write_b128 v138, v[40:43] offset:4480
	ds_write_b128 v138, v[36:39] offset:192
	ds_write_b128 v138, v[32:35] offset:4544
	ds_read_b128 v[222:225], v139 offset:0
	ds_read_b128 v[226:229], v139 offset:1088
	ds_read_b128 v[230:233], v139 offset:2176
	ds_read_b128 v[234:237], v139 offset:3264
	ds_read_b128 v[238:241], v139 offset:4352
	ds_read_b128 v[242:245], v139 offset:5440
	ds_read_b128 v[246:249], v139 offset:6528
	ds_read_b128 v[250:253], v139 offset:7616
	s_waitcnt lgkmcnt(0)
	s_waitcnt vmcnt(23)
	v_pk_add_f32 v[222:223], v[222:223], v[140:141]
	v_pk_add_f32 v[224:225], v[224:225], v[142:143]
	global_store_dwordx4 v130, v[222:225], s[10:11] offset:512
	s_waitcnt vmcnt(23)
; #define SCHED __builtin_amdgcn_sched_barrier(0)
; __device__ __forceinline__ void phase_gemm2(const Params& p, int layer, const float* xold, float* xnew) {
;     ...
; #pragma unroll
;     for (int ai = 0; ai < 2; ++ai)
; #pragma unroll
;       for (int bj = 0; bj < 2; ++bj) {
;         f32x4 xo[4][2];
; #pragma unroll
;         for (int m = 0; m < 4; ++m)
; #pragma unroll
;           for (int n = 0; n < 2; ++n) {
;             int feat = feat0 + ai * 128 + wr * 64 + m * 16 + fq * 4;
;             int tok = tok0 + bj * 128 + wc * 32 + n * 16 + fr;
;             xo[m][n] = *reinterpret_cast<const f32x4*>(xold + (size_t)tok * DM + feat);
;           }
;         SCHED;
; #pragma unroll
;         for (int m = 0; m < 4; ++m)
; #pragma unroll
;           for (int n = 0; n < 2; ++n) {
;             int feat = feat0 + ai * 128 + wr * 64 + m * 16 + fq * 4;
;             int tok = tok0 + bj * 128 + wc * 32 + n * 16 + fr;
;             *reinterpret_cast<f32x4*>(xnew + (size_t)tok * DM + feat) = xo[m][n] + acc[ai][bj][m][n];
;           }
;         SCHED;
;       }
	v_pk_add_f32 v[226:227], v[226:227], v[144:145]
	v_pk_add_f32 v[228:229], v[228:229], v[146:147]
	global_store_dwordx4 v131, v[226:229], s[10:11] offset:512
	s_waitcnt vmcnt(23)
	v_pk_add_f32 v[230:231], v[230:231], v[148:149]
	v_pk_add_f32 v[232:233], v[232:233], v[150:151]
	global_store_dwordx4 v132, v[230:233], s[10:11] offset:512
	s_waitcnt vmcnt(23)
	v_pk_add_f32 v[234:235], v[234:235], v[152:153]
	v_pk_add_f32 v[236:237], v[236:237], v[154:155]
	global_store_dwordx4 v133, v[234:237], s[10:11] offset:512
	s_waitcnt vmcnt(23)
	v_pk_add_f32 v[238:239], v[238:239], v[156:157]
	v_pk_add_f32 v[240:241], v[240:241], v[158:159]
	global_store_dwordx4 v134, v[238:241], s[10:11] offset:512
	s_waitcnt vmcnt(23)
	v_pk_add_f32 v[242:243], v[242:243], v[196:197]
	v_pk_add_f32 v[244:245], v[244:245], v[198:199]
	global_store_dwordx4 v135, v[242:245], s[10:11] offset:512
	s_waitcnt vmcnt(23)
	v_pk_add_f32 v[246:247], v[246:247], v[200:201]
	v_pk_add_f32 v[248:249], v[248:249], v[202:203]
	global_store_dwordx4 v136, v[246:249], s[10:11] offset:512
	s_waitcnt vmcnt(23)
	v_pk_add_f32 v[250:251], v[250:251], v[204:205]
	v_pk_add_f32 v[252:253], v[252:253], v[206:207]
	global_store_dwordx4 v137, v[250:253], s[10:11] offset:512
	s_add_u32 s14, s8, 0x200000
	s_addc_u32 s15, s9, 0
	global_load_dwordx4 v[140:143], v130, s[14:15] offset:512
	global_load_dwordx4 v[144:147], v131, s[14:15] offset:512
	global_load_dwordx4 v[148:151], v132, s[14:15] offset:512
	global_load_dwordx4 v[152:155], v133, s[14:15] offset:512
	global_load_dwordx4 v[156:159], v134, s[14:15] offset:512
	global_load_dwordx4 v[196:199], v135, s[14:15] offset:512
	global_load_dwordx4 v[200:203], v136, s[14:15] offset:512
	global_load_dwordx4 v[204:207], v137, s[14:15] offset:512
	ds_write_b128 v138, v[92:95] offset:0
	ds_write_b128 v138, v[88:91] offset:4352
	ds_write_b128 v138, v[84:87] offset:64
	ds_write_b128 v138, v[80:83] offset:4416
	ds_write_b128 v138, v[76:79] offset:128
	ds_write_b128 v138, v[72:75] offset:4480
	ds_write_b128 v138, v[68:71] offset:192
	ds_write_b128 v138, v[64:67] offset:4544
	ds_read_b128 v[222:225], v139 offset:0
	ds_read_b128 v[226:229], v139 offset:1088
	ds_read_b128 v[230:233], v139 offset:2176
	ds_read_b128 v[234:237], v139 offset:3264
	ds_read_b128 v[238:241], v139 offset:4352
	ds_read_b128 v[242:245], v139 offset:5440
	ds_read_b128 v[246:249], v139 offset:6528
	ds_read_b128 v[250:253], v139 offset:7616
	s_waitcnt lgkmcnt(0)
	s_waitcnt vmcnt(23)
	v_pk_add_f32 v[222:223], v[222:223], v[164:165]
	v_pk_add_f32 v[224:225], v[224:225], v[166:167]
	global_store_dwordx4 v130, v[222:225], s[16:17] offset:0
	s_waitcnt vmcnt(23)
	v_pk_add_f32 v[226:227], v[226:227], v[168:169]
	v_pk_add_f32 v[228:229], v[228:229], v[170:171]
	global_store_dwordx4 v131, v[226:229], s[16:17] offset:0
	s_waitcnt vmcnt(23)
	v_pk_add_f32 v[230:231], v[230:231], v[172:173]
	v_pk_add_f32 v[232:233], v[232:233], v[174:175]
	global_store_dwordx4 v132, v[230:233], s[16:17] offset:0
	s_waitcnt vmcnt(23)
	v_pk_add_f32 v[234:235], v[234:235], v[176:177]
	v_pk_add_f32 v[236:237], v[236:237], v[178:179]
	global_store_dwordx4 v133, v[234:237], s[16:17] offset:0
	s_waitcnt vmcnt(23)
	v_pk_add_f32 v[238:239], v[238:239], v[180:181]
	v_pk_add_f32 v[240:241], v[240:241], v[182:183]
	global_store_dwordx4 v134, v[238:241], s[16:17] offset:0
	s_waitcnt vmcnt(23)
	v_pk_add_f32 v[242:243], v[242:243], v[184:185]
	v_pk_add_f32 v[244:245], v[244:245], v[186:187]
	global_store_dwordx4 v135, v[242:245], s[16:17] offset:0
	s_waitcnt vmcnt(23)
	v_pk_add_f32 v[246:247], v[246:247], v[188:189]
	v_pk_add_f32 v[248:249], v[248:249], v[190:191]
	global_store_dwordx4 v136, v[246:249], s[16:17] offset:0
	s_waitcnt vmcnt(23)
	v_pk_add_f32 v[250:251], v[250:251], v[192:193]
	v_pk_add_f32 v[252:253], v[252:253], v[194:195]
	global_store_dwordx4 v137, v[250:253], s[16:17] offset:0
	ds_write_b128 v138, v[28:31] offset:0
	ds_write_b128 v138, v[24:27] offset:4352
	ds_write_b128 v138, v[20:23] offset:64
	ds_write_b128 v138, v[16:19] offset:4416
	ds_write_b128 v138, v[12:15] offset:128
	ds_write_b128 v138, v[8:11] offset:4480
	ds_write_b128 v138, v[4:7] offset:192
	ds_write_b128 v138, v[0:3] offset:4544
	ds_read_b128 v[222:225], v139 offset:0
	ds_read_b128 v[226:229], v139 offset:1088
	ds_read_b128 v[230:233], v139 offset:2176
	ds_read_b128 v[234:237], v139 offset:3264
	ds_read_b128 v[238:241], v139 offset:4352
	ds_read_b128 v[242:245], v139 offset:5440
	ds_read_b128 v[246:249], v139 offset:6528
	ds_read_b128 v[250:253], v139 offset:7616
	s_waitcnt lgkmcnt(0)
	s_waitcnt vmcnt(15)
	v_pk_add_f32 v[222:223], v[222:223], v[140:141]
	v_pk_add_f32 v[224:225], v[224:225], v[142:143]
	global_store_dwordx4 v130, v[222:225], s[16:17] offset:512
	s_waitcnt vmcnt(15)
	v_pk_add_f32 v[226:227], v[226:227], v[144:145]
	v_pk_add_f32 v[228:229], v[228:229], v[146:147]
	global_store_dwordx4 v131, v[226:229], s[16:17] offset:512
	s_waitcnt vmcnt(15)
	v_pk_add_f32 v[230:231], v[230:231], v[148:149]
	v_pk_add_f32 v[232:233], v[232:233], v[150:151]
	global_store_dwordx4 v132, v[230:233], s[16:17] offset:512
	s_waitcnt vmcnt(15)
	v_pk_add_f32 v[234:235], v[234:235], v[152:153]
	v_pk_add_f32 v[236:237], v[236:237], v[154:155]
	global_store_dwordx4 v133, v[234:237], s[16:17] offset:512
	s_waitcnt vmcnt(15)
	v_pk_add_f32 v[238:239], v[238:239], v[156:157]
	v_pk_add_f32 v[240:241], v[240:241], v[158:159]
	global_store_dwordx4 v134, v[238:241], s[16:17] offset:512
	s_waitcnt vmcnt(15)
	v_pk_add_f32 v[242:243], v[242:243], v[196:197]
	v_pk_add_f32 v[244:245], v[244:245], v[198:199]
	global_store_dwordx4 v135, v[242:245], s[16:17] offset:512
	s_waitcnt vmcnt(15)
	v_pk_add_f32 v[246:247], v[246:247], v[200:201]
	v_pk_add_f32 v[248:249], v[248:249], v[202:203]
	global_store_dwordx4 v136, v[246:249], s[16:17] offset:512
	s_waitcnt vmcnt(15)
	v_pk_add_f32 v[250:251], v[250:251], v[204:205]
	v_pk_add_f32 v[252:253], v[252:253], v[206:207]
	global_store_dwordx4 v137, v[250:253], s[16:17] offset:512
	s_load_dword s14, s[48:49], 0x0
	s_waitcnt lgkmcnt(0)
	s_add_i32 s30, s14, s30
	s_cmpk_gt_i32 s30, 0x1ff
	s_cbranch_scc1 .LBB0_47
